# v094 + work-queue preference: three XCDs (0,3,6) start on the FoX queue instead of two (0,4), after the DSA items got faster
# speedup vs baseline: 1.0110x; 1.0110x over previous
; #define LAS __attribute__((address_space(3)))
;     LAS int* sitem = (LAS int*)(lds + ITEM_OFF);
;     constexpr int N_D = 256, N_B = 2048, N_A = 128, N_C = 128, N_ALL = N_D + N_B + N_A + N_C;
;     const int pref = ((__builtin_amdgcn_s_getreg((3 << 11) | 20) & 3u) != 0u) ? 1 : 0;
;     auto fetch = [&]() -> int {
;         auto q1 = [&](int i) -> int { return i < N_A + N_C ? N_D + N_B + i : N_D + (i - (N_A + N_C)); };
;         if (pref == 0) { int i = (int)atomicAdd(ctr, 1u); if (i < N_D) return i; i = (int)atomicAdd(ctr + 32, 1u); return i < N_ALL - N_D ? q1(i) : N_ALL; }
;         int i = (int)atomicAdd(ctr + 32, 1u); if (i < N_ALL - N_D) return q1(i); i = (int)atomicAdd(ctr, 1u); return i < N_D ? i : N_ALL; };
;     int nxt = 0;
;     if (threadIdx.x == 0) nxt = fetch();
.LBB0_112:
	v_readlane_b32 s0, v253, 49
	v_readlane_b32 s1, v253, 50
	s_lshl_b32 s0, s0, 1
	v_readlane_b32 s1, v253, 51
	s_add_i32 s0, s0, s1
	s_ashr_i32 s1, s0, 31
	v_readlane_b32 s20, v251, 1
	s_lshl_b64 s[0:1], s[0:1], 2
	v_readlane_b32 s22, v251, 3
	v_readlane_b32 s23, v251, 4
	s_add_u32 s0, s22, s0
	s_addc_u32 s1, s23, s1
	v_writelane_b32 v253, s0, 55
	v_mov_b32_e32 v180, 0
	v_readlane_b32 s21, v251, 2
	v_writelane_b32 v253, s1, 56
	s_getreg_b32 s0, hwreg(HW_REG_XCC_ID, 0, 4)
	s_lshr_b32 s0, 0x49, s0
	s_and_b32 s0, s0, 1
	s_cmp_eq_u32 s0, 0
	s_cselect_b64 s[0:1], -1, 0
	v_writelane_b32 v253, s0, 57
	v_readlane_b32 s24, v251, 5
	v_readlane_b32 s25, v251, 6
	v_writelane_b32 v253, s1, 58
	v_readlane_b32 s26, v251, 7
	v_readlane_b32 s27, v251, 8
	s_mov_b64 s[0:1], exec
	v_readlane_b32 s20, v251, 13
	v_readlane_b32 s21, v251, 14
	s_and_b64 s[20:21], s[0:1], s[20:21]
	s_mov_b64 exec, s[20:21]
	s_cbranch_execz .LBB0_131
	v_readlane_b32 s20, v253, 57
	v_readlane_b32 s21, v253, 58
	s_and_b64 vcc, exec, s[20:21]
	s_cbranch_vccz .LBB0_123
	s_mov_b64 s[22:23], exec
	v_mbcnt_lo_u32_b32 v0, s22, 0
	v_mbcnt_hi_u32_b32 v0, s23, v0
	v_cmp_eq_u32_e32 vcc, 0, v0
	s_and_saveexec_b64 s[20:21], vcc
	s_cbranch_execz .LBB0_116
	s_bcnt1_i32_b64 s22, s[22:23]
	v_mov_b32_e32 v2, s22
	v_readlane_b32 s22, v253, 55
	v_readlane_b32 s23, v253, 56
	s_nop 4
	global_atomic_add v2, v1, v2, s[22:23] offset:128 sc0
